# barrier acquire hoisting: L1 invalidate issued together with the arrival atomic of quad/XCD barriers (the CU's L1 is idle while its workgroup is parked)
# baseline (speedup 1.0000x reference)
; __device__ __forceinline__ unsigned xb_ld(unsigned* p)              { return __hip_atomic_load(p, __ATOMIC_RELAXED, __HIP_MEMORY_SCOPE_AGENT); }
; __device__ __forceinline__ unsigned xb_add(unsigned* p, unsigned v) { return __hip_atomic_fetch_add(p, v, __ATOMIC_RELAXED, __HIP_MEMORY_SCOPE_AGENT); }
; #define XB_SPIN(cond, bar) do { unsigned _sp = 0; while (cond) { __builtin_amdgcn_s_sleep(1); \
;     if ((++_sp & 255u) == 0u) { if (xb_ld(&(bar)[XB_TMO])) break; if (_sp > XB_SPIN_CAP) { atomicAdd(&(bar)[XB_TMO], 1u); break; } } } } while (0)
; __device__ __forceinline__ void xcd_barrier(const XcdBarrier& b) {
;     ...
;         const unsigned old = xb_add(&bar[XB_XSUB(b.x)], 1u);
;         const unsigned gen = old / nloc;
;         if (old + 1u == (gen + 1u) * nloc) {
;             __builtin_amdgcn_fence(__ATOMIC_RELEASE, "agent");
;             asm volatile("s_waitcnt vmcnt(0)" ::: "memory");
;             const unsigned og = xb_add(&bar[XB_TOP], 1u);
;             const unsigned tg = og / nx;
;             if (og + 1u == (tg + 1u) * nx) xb_add(&bar[XB_TOPGEN], 1u);
;             else XB_SPIN(xb_ld(&bar[XB_TOPGEN]) == tg, bar);
;             __builtin_amdgcn_fence(__ATOMIC_ACQUIRE, "agent");
;             xb_add(&bar[XB_XGEN(b.x)], 1u);
;             asm volatile("s_waitcnt vmcnt(0)" ::: "memory");
;         } else {
;             XB_SPIN(xb_ld(&bar[XB_XGEN(b.x)]) == gen, bar);
;             __builtin_amdgcn_fence(__ATOMIC_ACQUIRE, "agent");
;             asm volatile("s_waitcnt vmcnt(0)" ::: "memory");
;         }
.Lxk_known_P2:
	s_cmp_eq_u32 s4, 1
	s_cbranch_scc0 .Lxg_P2
	v_readlane_b32 s10, v254, 30
	v_readlane_b32 s11, v254, 31
	s_and_b32 s12, s1, 15
	s_lshl_b32 s12, s12, 8
	s_add_u32 s6, s10, 0x300080
	s_addc_u32 s7, s11, 0
	s_add_u32 s6, s6, s12
	s_addc_u32 s7, s7, 0
	s_add_u32 s12, s10, 0x300008
	s_addc_u32 s13, s11, 0
	v_mov_b32_e32 v6, s12
	v_mov_b32_e32 v7, s13
	v_mov_b32_e32 v8, 1
	flat_atomic_add v[6:7], v8
	v_mov_b32_e32 v2, s6
	v_mov_b32_e32 v3, s7
	v_mov_b32_e32 v4, 1
	flat_atomic_add v4, v[2:3], v4 sc0
	buffer_inv sc1
	s_mov_b32 s8, 0
	s_waitcnt vmcnt(0) lgkmcnt(0)
	v_and_b32_e32 v4, 0xffffffe0, v4
	v_add_u32_e32 v4, 32, v4
.Lxl_spin_P2:
	flat_load_dword v5, v[2:3] sc1
	s_waitcnt vmcnt(0) lgkmcnt(0)
	v_cmp_lt_u32_e32 vcc, v5, v4
	s_cbranch_vccz .Lxl_done_P2
	s_sleep 1
	s_add_i32 s8, s8, 1
	s_cmp_lt_u32 s8, 0x100000
	s_cbranch_scc1 .Lxl_spin_P2
.Lxl_done_P2:
	s_branch .LBB0_729
.Lxg_P2:
	v_readlane_b32 s2, v253, 18
	s_waitcnt vmcnt(0) expcnt(0) lgkmcnt(0)
	s_and_b32 s1, s1, 15
	v_mov_b32_e32 v0, s2
	ds_read_b32 v2, v0
	v_readlane_b32 s2, v253, 19
	s_waitcnt lgkmcnt(0)
	v_cmp_ne_u32_e32 vcc, 0, v2
	v_mov_b32_e32 v0, s2
	ds_read_b32 v0, v0
	s_cbranch_vccnz .LBB0_699
	s_add_u32 s2, s42, 0x300200
	s_addc_u32 s3, s43, 0
	s_add_u32 s4, s42, 0x300400
	s_addc_u32 s5, s43, 0
	s_add_u32 s6, s42, 0x300500
	s_addc_u32 s7, s43, 0
	s_add_u32 s8, s42, 0x300600
	s_addc_u32 s9, s43, 0
	s_add_u32 s10, s42, 0x300700
	s_addc_u32 s11, s43, 0
	s_add_u32 s12, s42, 0x300800
	s_addc_u32 s13, s43, 0
	s_add_u32 s14, s42, 0x300900
	s_addc_u32 s15, s43, 0
	s_add_u32 s16, s42, 0x300a00
	s_addc_u32 s17, s43, 0
	s_add_u32 s18, s42, 0x300b00
	s_addc_u32 s19, s43, 0
	s_add_u32 s20, s42, 0x300c00
	s_addc_u32 s21, s43, 0
	s_add_u32 s22, s42, 0x300d00
	s_addc_u32 s23, s43, 0
	s_add_u32 s24, s42, 0x300e00
	s_addc_u32 s25, s43, 0
	s_add_u32 s26, s42, 0x300f00
	s_addc_u32 s27, s43, 0
	s_add_u32 s28, s42, 0x301000
	s_addc_u32 s29, s43, 0
	s_add_u32 s30, s42, 0x301100
	s_addc_u32 s31, s43, 0
	s_add_u32 s56, s42, 0x301200
	s_addc_u32 s57, s43, 0
	s_add_u32 s72, s42, 0x301300
	s_addc_u32 s73, s43, 0
	s_mov_b32 s39, 1
	s_mov_b64 s[74:75], 0
	s_branch .LBB0_689

; __device__ __forceinline__ unsigned xb_ld(unsigned* p)              { return __hip_atomic_load(p, __ATOMIC_RELAXED, __HIP_MEMORY_SCOPE_AGENT); }
; __device__ __forceinline__ unsigned xb_add(unsigned* p, unsigned v) { return __hip_atomic_fetch_add(p, v, __ATOMIC_RELAXED, __HIP_MEMORY_SCOPE_AGENT); }
; #define XB_SPIN(cond, bar) do { unsigned _sp = 0; while (cond) { __builtin_amdgcn_s_sleep(1); \
;     if ((++_sp & 255u) == 0u) { if (xb_ld(&(bar)[XB_TMO])) break; if (_sp > XB_SPIN_CAP) { atomicAdd(&(bar)[XB_TMO], 1u); break; } } } } while (0)
; __device__ __forceinline__ void xcd_barrier(const XcdBarrier& b) {
;     ...
;         const unsigned old = xb_add(&bar[XB_XSUB(b.x)], 1u);
;         const unsigned gen = old / nloc;
;         if (old + 1u == (gen + 1u) * nloc) {
;             __builtin_amdgcn_fence(__ATOMIC_RELEASE, "agent");
;             asm volatile("s_waitcnt vmcnt(0)" ::: "memory");
;             const unsigned og = xb_add(&bar[XB_TOP], 1u);
;             const unsigned tg = og / nx;
;             if (og + 1u == (tg + 1u) * nx) xb_add(&bar[XB_TOPGEN], 1u);
;             else XB_SPIN(xb_ld(&bar[XB_TOPGEN]) == tg, bar);
;             __builtin_amdgcn_fence(__ATOMIC_ACQUIRE, "agent");
;             xb_add(&bar[XB_XGEN(b.x)], 1u);
;             asm volatile("s_waitcnt vmcnt(0)" ::: "memory");
;         } else {
;             XB_SPIN(xb_ld(&bar[XB_XGEN(b.x)]) == gen, bar);
;             __builtin_amdgcn_fence(__ATOMIC_ACQUIRE, "agent");
;             asm volatile("s_waitcnt vmcnt(0)" ::: "memory");
;         }
.LBB0_785:
	v_readlane_b32 s4, v254, 16
	v_readlane_b32 s18, v254, 30
	v_readlane_b32 s19, v254, 31
	s_mov_b64 s[72:73], s[18:19]
	s_getreg_b32 s1, hwreg(HW_REG_XCC_ID, 0, 4)
	s_waitcnt vmcnt(0)
	v_readlane_b32 s5, v254, 17
	v_readlane_b32 s6, v254, 18
	v_readlane_b32 s7, v254, 19
	v_readlane_b32 s8, v254, 20
	v_readlane_b32 s9, v254, 21
	v_readlane_b32 s10, v254, 22
	v_readlane_b32 s11, v254, 23
	v_readlane_b32 s12, v254, 24
	v_readlane_b32 s13, v254, 25
	v_readlane_b32 s14, v254, 26
	v_readlane_b32 s15, v254, 27
	v_readlane_b32 s16, v254, 28
	v_readlane_b32 s17, v254, 29
	s_barrier
	s_mov_b64 s[42:43], exec
	v_readlane_b32 s4, v254, 32
	v_readlane_b32 s5, v254, 33
	s_and_b64 s[4:5], s[42:43], s[4:5]
	s_mov_b64 exec, s[4:5]
	s_cbranch_execz .LBB0_829
	s_waitcnt vmcnt(0) lgkmcnt(0)
	v_mov_b32_e32 v0, 0x20008
	ds_read_b32 v2, v0
	s_waitcnt lgkmcnt(0)
	v_readfirstlane_b32 s4, v2
	s_nop 3
	s_cmp_eq_u32 s4, 1
	s_cbranch_scc0 .Lxg_P3
	v_readlane_b32 s10, v254, 30
	v_readlane_b32 s11, v254, 31
	s_and_b32 s12, s33, 7
	s_lshr_b32 s13, s33, 3
	s_and_b32 s13, s13, 7
	s_lshl_b32 s12, s12, 3
	s_or_b32 s12, s12, s13
	s_and_b32 s13, s12, 15
	s_lshl_b32 s13, s13, 8
	s_lshr_b32 s12, s12, 4
	s_lshl_b32 s12, s12, 2
	s_add_u32 s12, s12, s13
	s_add_u32 s6, s10, 0x300010
	s_addc_u32 s7, s11, 0
	s_add_u32 s6, s6, s12
	s_addc_u32 s7, s7, 0
	v_mov_b32_e32 v2, s6
	v_mov_b32_e32 v3, s7
	v_mov_b32_e32 v4, 1
	flat_atomic_add v4, v[2:3], v4 sc0
	buffer_inv sc1
	s_mov_b32 s8, 0
	s_waitcnt vmcnt(0) lgkmcnt(0)
	v_and_b32_e32 v4, 0xfffffffc, v4
	v_add_u32_e32 v4, 4, v4
.Lxl_spin_P3:
	flat_load_dword v5, v[2:3] sc1
	s_waitcnt vmcnt(0) lgkmcnt(0)
	v_cmp_lt_u32_e32 vcc, v5, v4
	s_cbranch_vccz .Lxl_done_P3
	s_sleep 1
	s_add_i32 s8, s8, 1
	s_cmp_lt_u32 s8, 0x100000
	s_cbranch_scc1 .Lxl_spin_P3
.Lxl_done_P3:
	s_branch .LBB0_829
.Lxg_P3:
	v_readlane_b32 s4, v253, 18
	s_waitcnt vmcnt(0) expcnt(0) lgkmcnt(0)
	s_and_b32 s1, s1, 15
	v_mov_b32_e32 v0, s4
	ds_read_b32 v2, v0
	v_readlane_b32 s4, v253, 19
	s_waitcnt lgkmcnt(0)
	v_cmp_ne_u32_e32 vcc, 0, v2
	v_mov_b32_e32 v0, s4
	ds_read_b32 v0, v0
	s_cbranch_vccnz .LBB0_800
	s_add_u32 s4, s72, 0x300200
	s_addc_u32 s5, s73, 0
	s_add_u32 s6, s72, 0x300400
	s_addc_u32 s7, s73, 0
	s_add_u32 s8, s72, 0x300500
	s_addc_u32 s9, s73, 0
	s_add_u32 s10, s72, 0x300600
	s_addc_u32 s11, s73, 0
	s_add_u32 s12, s72, 0x300700
	s_addc_u32 s13, s73, 0
	s_add_u32 s14, s72, 0x300800
	s_addc_u32 s15, s73, 0
	s_add_u32 s16, s72, 0x300900
	s_addc_u32 s17, s73, 0
	s_add_u32 s18, s72, 0x300a00
	s_addc_u32 s19, s73, 0
	s_add_u32 s20, s72, 0x300b00
	s_addc_u32 s21, s73, 0
	s_add_u32 s22, s72, 0x300c00
	s_addc_u32 s23, s73, 0
	s_add_u32 s24, s72, 0x300d00
	s_addc_u32 s25, s73, 0
	s_add_u32 s26, s72, 0x300e00
	s_addc_u32 s27, s73, 0
	s_add_u32 s28, s72, 0x300f00
	s_addc_u32 s29, s73, 0
	s_add_u32 s30, s72, 0x301000
	s_addc_u32 s31, s73, 0
	s_add_u32 s34, s72, 0x301100
	s_addc_u32 s35, s73, 0
	s_add_u32 s56, s72, 0x301200
	s_addc_u32 s57, s73, 0
	s_add_u32 s74, s72, 0x301300
	s_addc_u32 s75, s73, 0
	s_mov_b32 s39, 1
	s_mov_b64 s[94:95], 0
	s_branch .LBB0_790

; __device__ __forceinline__ unsigned xb_ld(unsigned* p)              { return __hip_atomic_load(p, __ATOMIC_RELAXED, __HIP_MEMORY_SCOPE_AGENT); }
; __device__ __forceinline__ unsigned xb_add(unsigned* p, unsigned v) { return __hip_atomic_fetch_add(p, v, __ATOMIC_RELAXED, __HIP_MEMORY_SCOPE_AGENT); }
; #define XB_SPIN(cond, bar) do { unsigned _sp = 0; while (cond) { __builtin_amdgcn_s_sleep(1); \
;     if ((++_sp & 255u) == 0u) { if (xb_ld(&(bar)[XB_TMO])) break; if (_sp > XB_SPIN_CAP) { atomicAdd(&(bar)[XB_TMO], 1u); break; } } } } while (0)
; __device__ __forceinline__ void xcd_barrier(const XcdBarrier& b) {
;     ...
;         const unsigned old = xb_add(&bar[XB_XSUB(b.x)], 1u);
;         const unsigned gen = old / nloc;
;         if (old + 1u == (gen + 1u) * nloc) {
;             __builtin_amdgcn_fence(__ATOMIC_RELEASE, "agent");
;             asm volatile("s_waitcnt vmcnt(0)" ::: "memory");
;             const unsigned og = xb_add(&bar[XB_TOP], 1u);
;             const unsigned tg = og / nx;
;             if (og + 1u == (tg + 1u) * nx) xb_add(&bar[XB_TOPGEN], 1u);
;             else XB_SPIN(xb_ld(&bar[XB_TOPGEN]) == tg, bar);
;             __builtin_amdgcn_fence(__ATOMIC_ACQUIRE, "agent");
;             xb_add(&bar[XB_XGEN(b.x)], 1u);
;             asm volatile("s_waitcnt vmcnt(0)" ::: "memory");
;         } else {
;             XB_SPIN(xb_ld(&bar[XB_XGEN(b.x)]) == gen, bar);
;             __builtin_amdgcn_fence(__ATOMIC_ACQUIRE, "agent");
;             asm volatile("s_waitcnt vmcnt(0)" ::: "memory");
;         }
.LBB0_867:
	v_readlane_b32 s4, v254, 16
	v_readlane_b32 s18, v254, 30
	v_readlane_b32 s19, v254, 31
	s_mov_b64 s[72:73], s[18:19]
	s_getreg_b32 s1, hwreg(HW_REG_XCC_ID, 0, 4)
	s_waitcnt vmcnt(0)
	v_readlane_b32 s5, v254, 17
	v_readlane_b32 s6, v254, 18
	v_readlane_b32 s7, v254, 19
	v_readlane_b32 s8, v254, 20
	v_readlane_b32 s9, v254, 21
	v_readlane_b32 s10, v254, 22
	v_readlane_b32 s11, v254, 23
	v_readlane_b32 s12, v254, 24
	v_readlane_b32 s13, v254, 25
	v_readlane_b32 s14, v254, 26
	v_readlane_b32 s15, v254, 27
	v_readlane_b32 s16, v254, 28
	v_readlane_b32 s17, v254, 29
	s_barrier
	s_mov_b64 s[42:43], exec
	v_readlane_b32 s4, v254, 32
	v_readlane_b32 s5, v254, 33
	s_and_b64 s[4:5], s[42:43], s[4:5]
	s_mov_b64 exec, s[4:5]
	s_cbranch_execz .LBB0_911
	s_waitcnt vmcnt(0) lgkmcnt(0)
	v_mov_b32_e32 v0, 0x20008
	ds_read_b32 v2, v0
	s_waitcnt lgkmcnt(0)
	v_readfirstlane_b32 s4, v2
	s_nop 3
	s_cmp_eq_u32 s4, 1
	s_cbranch_scc0 .Lxg_P4
	v_readlane_b32 s10, v254, 30
	v_readlane_b32 s11, v254, 31
	s_and_b32 s12, s33, 7
	s_lshr_b32 s13, s33, 3
	s_and_b32 s13, s13, 7
	s_lshl_b32 s12, s12, 3
	s_or_b32 s12, s12, s13
	s_and_b32 s13, s12, 15
	s_lshl_b32 s13, s13, 8
	s_lshr_b32 s12, s12, 4
	s_lshl_b32 s12, s12, 2
	s_add_u32 s12, s12, s13
	s_add_u32 s6, s10, 0x300010
	s_addc_u32 s7, s11, 0
	s_add_u32 s6, s6, s12
	s_addc_u32 s7, s7, 0
	s_add_u32 s12, s10, 0x300008
	s_addc_u32 s13, s11, 0
	v_mov_b32_e32 v6, s12
	v_mov_b32_e32 v7, s13
	v_readlane_b32 s12, v253, 22
	s_nop 3
	s_lshl_b32 s12, s12, 2
	s_add_i32 s12, s12, s44
	s_add_i32 s12, s12, 1
	s_lshl_b32 s12, s12, 8
	v_mov_b32_e32 v9, s12
	v_mov_b32_e32 v2, s6
	v_mov_b32_e32 v3, s7
	v_mov_b32_e32 v4, 1
	flat_atomic_add v4, v[2:3], v4 sc0
	buffer_inv sc1
	s_mov_b32 s8, 0
	s_waitcnt vmcnt(0) lgkmcnt(0)
	v_and_b32_e32 v4, 0xfffffffc, v4
	v_add_u32_e32 v4, 4, v4
.Lxl_spin_P4:
	flat_load_dword v5, v[2:3] sc1
	flat_load_dword v10, v[6:7] sc1
	s_waitcnt vmcnt(0) lgkmcnt(0)
	v_cmp_lt_u32_e32 vcc, v5, v4
	v_cmp_lt_u32_e64 s[14:15], v10, v9
	s_or_b64 vcc, vcc, s[14:15]
	s_cbranch_vccz .Lxl_done_P4
	s_sleep 1
	s_add_i32 s8, s8, 1
	s_cmp_lt_u32 s8, 0x100000
	s_cbranch_scc1 .Lxl_spin_P4
.Lxl_done_P4:
	s_branch .LBB0_911
.Lxg_P4:
	v_readlane_b32 s4, v253, 18
	s_waitcnt vmcnt(0) expcnt(0) lgkmcnt(0)
	s_and_b32 s1, s1, 15
	v_mov_b32_e32 v0, s4
	ds_read_b32 v2, v0
	v_readlane_b32 s4, v253, 19
	s_waitcnt lgkmcnt(0)
	v_cmp_ne_u32_e32 vcc, 0, v2
	v_mov_b32_e32 v0, s4
	ds_read_b32 v0, v0
	s_cbranch_vccnz .LBB0_882
	s_add_u32 s4, s72, 0x300200
	s_addc_u32 s5, s73, 0
	s_add_u32 s6, s72, 0x300400
	s_addc_u32 s7, s73, 0
	s_add_u32 s8, s72, 0x300500
	s_addc_u32 s9, s73, 0
	s_add_u32 s10, s72, 0x300600
	s_addc_u32 s11, s73, 0
	s_add_u32 s12, s72, 0x300700
	s_addc_u32 s13, s73, 0
	s_add_u32 s14, s72, 0x300800
	s_addc_u32 s15, s73, 0
	s_add_u32 s16, s72, 0x300900
	s_addc_u32 s17, s73, 0
	s_add_u32 s18, s72, 0x300a00
	s_addc_u32 s19, s73, 0
	s_add_u32 s20, s72, 0x300b00
	s_addc_u32 s21, s73, 0
	s_add_u32 s22, s72, 0x300c00
	s_addc_u32 s23, s73, 0
	s_add_u32 s24, s72, 0x300d00
	s_addc_u32 s25, s73, 0
	s_add_u32 s26, s72, 0x300e00
	s_addc_u32 s27, s73, 0
	s_add_u32 s28, s72, 0x300f00
	s_addc_u32 s29, s73, 0
	s_add_u32 s30, s72, 0x301000
	s_addc_u32 s31, s73, 0
	s_add_u32 s34, s72, 0x301100
	s_addc_u32 s35, s73, 0
	s_add_u32 s56, s72, 0x301200
	s_addc_u32 s57, s73, 0
	s_add_u32 s74, s72, 0x301300
	s_addc_u32 s75, s73, 0
	s_mov_b32 s39, 1
	s_mov_b64 s[94:95], 0
	s_branch .LBB0_872

; __device__ __forceinline__ unsigned xb_ld(unsigned* p)              { return __hip_atomic_load(p, __ATOMIC_RELAXED, __HIP_MEMORY_SCOPE_AGENT); }
; __device__ __forceinline__ unsigned xb_add(unsigned* p, unsigned v) { return __hip_atomic_fetch_add(p, v, __ATOMIC_RELAXED, __HIP_MEMORY_SCOPE_AGENT); }
; #define XB_SPIN(cond, bar) do { unsigned _sp = 0; while (cond) { __builtin_amdgcn_s_sleep(1); \
;     if ((++_sp & 255u) == 0u) { if (xb_ld(&(bar)[XB_TMO])) break; if (_sp > XB_SPIN_CAP) { atomicAdd(&(bar)[XB_TMO], 1u); break; } } } } while (0)
; __device__ __forceinline__ void xcd_barrier(const XcdBarrier& b) {
;     ...
;         const unsigned old = xb_add(&bar[XB_XSUB(b.x)], 1u);
;         const unsigned gen = old / nloc;
;         if (old + 1u == (gen + 1u) * nloc) {
;             __builtin_amdgcn_fence(__ATOMIC_RELEASE, "agent");
;             asm volatile("s_waitcnt vmcnt(0)" ::: "memory");
;             const unsigned og = xb_add(&bar[XB_TOP], 1u);
;             const unsigned tg = og / nx;
;             if (og + 1u == (tg + 1u) * nx) xb_add(&bar[XB_TOPGEN], 1u);
;             else XB_SPIN(xb_ld(&bar[XB_TOPGEN]) == tg, bar);
;             __builtin_amdgcn_fence(__ATOMIC_ACQUIRE, "agent");
;             xb_add(&bar[XB_XGEN(b.x)], 1u);
;             asm volatile("s_waitcnt vmcnt(0)" ::: "memory");
;         } else {
;             XB_SPIN(xb_ld(&bar[XB_XGEN(b.x)]) == gen, bar);
;             __builtin_amdgcn_fence(__ATOMIC_ACQUIRE, "agent");
;             asm volatile("s_waitcnt vmcnt(0)" ::: "memory");
;         }
.LBB0_931:
	v_readlane_b32 s4, v254, 16
	v_readlane_b32 s18, v254, 30
	v_readlane_b32 s19, v254, 31
	s_mov_b64 s[72:73], s[18:19]
	s_getreg_b32 s1, hwreg(HW_REG_XCC_ID, 0, 4)
	s_waitcnt vmcnt(0)
	v_readlane_b32 s5, v254, 17
	v_readlane_b32 s6, v254, 18
	v_readlane_b32 s7, v254, 19
	v_readlane_b32 s8, v254, 20
	v_readlane_b32 s9, v254, 21
	v_readlane_b32 s10, v254, 22
	v_readlane_b32 s11, v254, 23
	v_readlane_b32 s12, v254, 24
	v_readlane_b32 s13, v254, 25
	v_readlane_b32 s14, v254, 26
	v_readlane_b32 s15, v254, 27
	v_readlane_b32 s16, v254, 28
	v_readlane_b32 s17, v254, 29
	s_barrier
	s_mov_b64 s[4:5], exec
	v_readlane_b32 s6, v254, 32
	v_readlane_b32 s7, v254, 33
	s_and_b64 s[6:7], s[4:5], s[6:7]
	s_xor_b64 s[42:43], s[6:7], s[4:5]
	s_mov_b64 exec, s[6:7]
	s_cbranch_execz .LBB0_976
	s_waitcnt vmcnt(0) lgkmcnt(0)
	v_mov_b32_e32 v0, 0x20008
	ds_read_b32 v2, v0
	s_waitcnt lgkmcnt(0)
	v_readfirstlane_b32 s4, v2
	s_nop 3
	s_cmp_eq_u32 s4, 1
	s_cbranch_scc0 .Lxg_P5
	v_readlane_b32 s10, v254, 30
	v_readlane_b32 s11, v254, 31
	s_and_b32 s12, s33, 7
	s_lshr_b32 s13, s33, 3
	s_and_b32 s13, s13, 7
	s_lshl_b32 s12, s12, 3
	s_or_b32 s12, s12, s13
	s_and_b32 s13, s12, 15
	s_lshl_b32 s13, s13, 8
	s_lshr_b32 s12, s12, 4
	s_lshl_b32 s12, s12, 2
	s_add_u32 s12, s12, s13
	s_add_u32 s6, s10, 0x300010
	s_addc_u32 s7, s11, 0
	s_add_u32 s6, s6, s12
	s_addc_u32 s7, s7, 0
	v_mov_b32_e32 v2, s6
	v_mov_b32_e32 v3, s7
	v_mov_b32_e32 v4, 1
	flat_atomic_add v4, v[2:3], v4 sc0
	buffer_inv sc1
	s_mov_b32 s8, 0
	s_waitcnt vmcnt(0) lgkmcnt(0)
	v_and_b32_e32 v4, 0xfffffffc, v4
	v_add_u32_e32 v4, 4, v4
.Lxl_spin_P5:
	flat_load_dword v5, v[2:3] sc1
	s_waitcnt vmcnt(0) lgkmcnt(0)
	v_cmp_lt_u32_e32 vcc, v5, v4
	s_cbranch_vccz .Lxl_done_P5
	s_sleep 1
	s_add_i32 s8, s8, 1
	s_cmp_lt_u32 s8, 0x100000
	s_cbranch_scc1 .Lxl_spin_P5
.Lxl_done_P5:
	s_branch .LBB0_976
.Lxg_P5:
	v_readlane_b32 s4, v253, 18
	s_waitcnt vmcnt(0) expcnt(0) lgkmcnt(0)
	s_and_b32 s1, s1, 15
	v_mov_b32_e32 v0, s4
	ds_read_b32 v2, v0
	v_readlane_b32 s4, v253, 19
	s_waitcnt lgkmcnt(0)
	v_cmp_ne_u32_e32 vcc, 0, v2
	v_mov_b32_e32 v0, s4
	ds_read_b32 v0, v0
	s_cbranch_vccnz .LBB0_946
	s_add_u32 s4, s72, 0x300200
	s_addc_u32 s5, s73, 0
	s_add_u32 s6, s72, 0x300400
	s_addc_u32 s7, s73, 0
	s_add_u32 s8, s72, 0x300500
	s_addc_u32 s9, s73, 0
	s_add_u32 s10, s72, 0x300600
	s_addc_u32 s11, s73, 0
	s_add_u32 s12, s72, 0x300700
	s_addc_u32 s13, s73, 0
	s_add_u32 s14, s72, 0x300800
	s_addc_u32 s15, s73, 0
	s_add_u32 s16, s72, 0x300900
	s_addc_u32 s17, s73, 0
	s_add_u32 s18, s72, 0x300a00
	s_addc_u32 s19, s73, 0
	s_add_u32 s20, s72, 0x300b00
	s_addc_u32 s21, s73, 0
	s_add_u32 s22, s72, 0x300c00
	s_addc_u32 s23, s73, 0
	s_add_u32 s24, s72, 0x300d00
	s_addc_u32 s25, s73, 0
	s_add_u32 s26, s72, 0x300e00
	s_addc_u32 s27, s73, 0
	s_add_u32 s28, s72, 0x300f00
	s_addc_u32 s29, s73, 0
	s_add_u32 s30, s72, 0x301000
	s_addc_u32 s31, s73, 0
	s_add_u32 s34, s72, 0x301100
	s_addc_u32 s35, s73, 0
	s_add_u32 s56, s72, 0x301200
	s_addc_u32 s57, s73, 0
	s_add_u32 s74, s72, 0x301300
	s_addc_u32 s75, s73, 0
	s_mov_b32 s39, 1
	s_mov_b64 s[94:95], 0
	s_branch .LBB0_936

; __device__ __forceinline__ unsigned xb_ld(unsigned* p)              { return __hip_atomic_load(p, __ATOMIC_RELAXED, __HIP_MEMORY_SCOPE_AGENT); }
; __device__ __forceinline__ unsigned xb_add(unsigned* p, unsigned v) { return __hip_atomic_fetch_add(p, v, __ATOMIC_RELAXED, __HIP_MEMORY_SCOPE_AGENT); }
; #define XB_SPIN(cond, bar) do { unsigned _sp = 0; while (cond) { __builtin_amdgcn_s_sleep(1); \
;     if ((++_sp & 255u) == 0u) { if (xb_ld(&(bar)[XB_TMO])) break; if (_sp > XB_SPIN_CAP) { atomicAdd(&(bar)[XB_TMO], 1u); break; } } } } while (0)
; __device__ __forceinline__ void xcd_barrier(const XcdBarrier& b) {
;     ...
;         const unsigned old = xb_add(&bar[XB_XSUB(b.x)], 1u);
;         const unsigned gen = old / nloc;
;         if (old + 1u == (gen + 1u) * nloc) {
;             __builtin_amdgcn_fence(__ATOMIC_RELEASE, "agent");
;             asm volatile("s_waitcnt vmcnt(0)" ::: "memory");
;             const unsigned og = xb_add(&bar[XB_TOP], 1u);
;             const unsigned tg = og / nx;
;             if (og + 1u == (tg + 1u) * nx) xb_add(&bar[XB_TOPGEN], 1u);
;             else XB_SPIN(xb_ld(&bar[XB_TOPGEN]) == tg, bar);
;             __builtin_amdgcn_fence(__ATOMIC_ACQUIRE, "agent");
;             xb_add(&bar[XB_XGEN(b.x)], 1u);
;             asm volatile("s_waitcnt vmcnt(0)" ::: "memory");
;         } else {
;             XB_SPIN(xb_ld(&bar[XB_XGEN(b.x)]) == gen, bar);
;             __builtin_amdgcn_fence(__ATOMIC_ACQUIRE, "agent");
;             asm volatile("s_waitcnt vmcnt(0)" ::: "memory");
;         }
.LBB0_1014:
	v_readlane_b32 s0, v254, 16
	v_readlane_b32 s14, v254, 30
	v_readlane_b32 s15, v254, 31
	s_mov_b64 s[42:43], s[14:15]
	s_getreg_b32 s0, hwreg(HW_REG_XCC_ID, 0, 4)
	s_waitcnt vmcnt(0)
	v_readlane_b32 s1, v254, 17
	v_readlane_b32 s2, v254, 18
	v_readlane_b32 s3, v254, 19
	v_readlane_b32 s4, v254, 20
	v_readlane_b32 s5, v254, 21
	v_readlane_b32 s6, v254, 22
	v_readlane_b32 s7, v254, 23
	v_readlane_b32 s8, v254, 24
	v_readlane_b32 s9, v254, 25
	v_readlane_b32 s10, v254, 26
	v_readlane_b32 s11, v254, 27
	v_readlane_b32 s12, v254, 28
	v_readlane_b32 s13, v254, 29
	s_barrier
	s_mov_b64 s[34:35], exec
	v_readlane_b32 s2, v254, 32
	v_readlane_b32 s3, v254, 33
	s_and_b64 s[2:3], s[34:35], s[2:3]
	s_mov_b64 exec, s[2:3]
	s_cbranch_execz .LBB0_183
	s_waitcnt vmcnt(0) lgkmcnt(0)
	v_mov_b32_e32 v0, 0x20008
	ds_read_b32 v2, v0
	s_waitcnt lgkmcnt(0)
	v_readfirstlane_b32 s4, v2
	s_nop 3
	s_cmp_eq_u32 s44, 3
	s_cbranch_scc1 .Lxg_P6
	s_cmp_eq_u32 s4, 1
	s_cbranch_scc0 .Lxg_P6
	v_readlane_b32 s10, v254, 30
	v_readlane_b32 s11, v254, 31
	s_and_b32 s12, s33, 7
	s_lshr_b32 s13, s33, 3
	s_and_b32 s13, s13, 7
	s_lshl_b32 s12, s12, 3
	s_or_b32 s12, s12, s13
	s_and_b32 s13, s12, 15
	s_lshl_b32 s13, s13, 8
	s_lshr_b32 s12, s12, 4
	s_lshl_b32 s12, s12, 2
	s_add_u32 s12, s12, s13
	s_add_u32 s6, s10, 0x300010
	s_addc_u32 s7, s11, 0
	s_add_u32 s6, s6, s12
	s_addc_u32 s7, s7, 0
	s_add_u32 s12, s10, 0x30000c
	s_addc_u32 s13, s11, 0
	v_mov_b32_e32 v6, s12
	v_mov_b32_e32 v7, s13
	v_mov_b32_e32 v8, 1
	flat_atomic_add v[6:7], v8
	v_mov_b32_e32 v2, s6
	v_mov_b32_e32 v3, s7
	v_mov_b32_e32 v4, 1
	flat_atomic_add v4, v[2:3], v4 sc0
	buffer_inv sc1
	s_mov_b32 s8, 0
	s_waitcnt vmcnt(0) lgkmcnt(0)
	v_and_b32_e32 v4, 0xfffffffc, v4
	v_add_u32_e32 v4, 4, v4
.Lxl_spin_P6:
	flat_load_dword v5, v[2:3] sc1
	s_waitcnt vmcnt(0) lgkmcnt(0)
	v_cmp_lt_u32_e32 vcc, v5, v4
	s_cbranch_vccz .Lxl_done_P6
	s_sleep 1
	s_add_i32 s8, s8, 1
	s_cmp_lt_u32 s8, 0x100000
	s_cbranch_scc1 .Lxl_spin_P6
.Lxl_done_P6:
	s_branch .LBB0_183
.Lxg_P6:
	v_readlane_b32 s1, v253, 18
	s_waitcnt vmcnt(0) expcnt(0) lgkmcnt(0)
	s_and_b32 s0, s0, 15
	v_mov_b32_e32 v0, s1
	ds_read_b32 v2, v0
	v_readlane_b32 s1, v253, 19
	s_waitcnt lgkmcnt(0)
	v_cmp_ne_u32_e32 vcc, 0, v2
	v_mov_b32_e32 v0, s1
	ds_read_b32 v0, v0
	s_cbranch_vccnz .LBB0_1029
	s_add_u32 s2, s42, 0x300200
	s_addc_u32 s3, s43, 0
	s_add_u32 s4, s42, 0x300400
	s_addc_u32 s5, s43, 0
	s_add_u32 s6, s42, 0x300500
	s_addc_u32 s7, s43, 0
	s_add_u32 s8, s42, 0x300600
	s_addc_u32 s9, s43, 0
	s_add_u32 s10, s42, 0x300700
	s_addc_u32 s11, s43, 0
	s_add_u32 s12, s42, 0x300800
	s_addc_u32 s13, s43, 0
	s_add_u32 s14, s42, 0x300900
	s_addc_u32 s15, s43, 0
	s_add_u32 s16, s42, 0x300a00
	s_addc_u32 s17, s43, 0
	s_add_u32 s18, s42, 0x300b00
	s_addc_u32 s19, s43, 0
	s_add_u32 s20, s42, 0x300c00
	s_addc_u32 s21, s43, 0
	s_add_u32 s22, s42, 0x300d00
	s_addc_u32 s23, s43, 0
	s_add_u32 s24, s42, 0x300e00
	s_addc_u32 s25, s43, 0
	s_add_u32 s26, s42, 0x300f00
	s_addc_u32 s27, s43, 0
	s_add_u32 s28, s42, 0x301000
	s_addc_u32 s29, s43, 0
	s_add_u32 s30, s42, 0x301100
	s_addc_u32 s31, s43, 0
	s_add_u32 s56, s42, 0x301200
	s_addc_u32 s57, s43, 0
	s_add_u32 s72, s42, 0x301300
	s_addc_u32 s73, s43, 0
	s_mov_b32 s1, 1
	s_mov_b64 s[74:75], 0
	s_branch .LBB0_1019
